# stack6 + B_MIX: Ws block, LayerNorm parameter and v-row loads of a unit issued together at the unit top (before the seam barrier and the statistics stage)
# speedup vs baseline: 1.0030x; 1.0030x over previous
.LBB0_144:
	s_ashr_i32 s2, s12, 3
	s_and_b32 s0, s2, 0xffffffe0
	v_readlane_b32 s1, v250, 9
	s_add_i32 s0, s0, s1
	s_ashr_i32 s0, s0, 3
	v_readlane_b32 s1, v250, 3
	s_add_i32 s3, s0, s1
	v_readlane_b32 s0, v250, 36
	v_readlane_b32 s1, v250, 37
	s_and_b64 s[0:1], s[0:1], exec
	s_cselect_b32 s14, s3, s2
	v_readlane_b32 s0, v250, 36
	v_readlane_b32 s1, v250, 37
	s_and_b64 s[0:1], s[0:1], exec
	v_readlane_b32 s0, v250, 9
	s_cselect_b32 s0, s0, s12
	s_and_b32 s13, s0, 7
	s_lshl_b32 s15, s13, 7
	v_mov_b32_e32 v181, 0
	v_ashrrev_i32_e32 v184, 4, v78
	v_add_u32_e32 v186, s15, v184
	v_ashrrev_i32_e32 v187, 31, v186
	v_lshlrev_b32_e32 v180, 1, v80
	v_lshlrev_b64 v[186:187], 8, v[186:187]
	v_and_b32_e32 v180, 0xf0, v180
	v_lshl_add_u64 v[186:187], s[98:99], 0, v[186:187]
	v_lshl_add_u64 v[186:187], v[186:187], 0, v[180:181]
	global_load_dwordx4 v[160:163], v[186:187], off
	s_movk_i32 s16, 0x110
	v_mul_lo_u32 v184, v184, s16
	v_add3_u32 v176, s23, v184, v180
	v_add_u32_e32 v182, 0x200, v78
	v_add_u32_e32 v183, 0x1000, v80
	v_ashrrev_i32_e32 v184, 4, v182
	v_add_u32_e32 v186, s15, v184
	v_ashrrev_i32_e32 v187, 31, v186
	v_lshlrev_b32_e32 v180, 1, v183
	v_lshlrev_b64 v[186:187], 8, v[186:187]
	v_and_b32_e32 v180, 0xf0, v180
	v_lshl_add_u64 v[186:187], s[98:99], 0, v[186:187]
	v_lshl_add_u64 v[186:187], v[186:187], 0, v[180:181]
	global_load_dwordx4 v[164:167], v[186:187], off
	v_mul_lo_u32 v184, v184, s16
	v_add3_u32 v177, s23, v184, v180
	v_add_u32_e32 v182, 0x400, v78
	v_add_u32_e32 v183, 0x2000, v80
	v_ashrrev_i32_e32 v184, 4, v182
	v_add_u32_e32 v186, s15, v184
	v_ashrrev_i32_e32 v187, 31, v186
	v_lshlrev_b32_e32 v180, 1, v183
	v_lshlrev_b64 v[186:187], 8, v[186:187]
	v_and_b32_e32 v180, 0xf0, v180
	v_lshl_add_u64 v[186:187], s[98:99], 0, v[186:187]
	v_lshl_add_u64 v[186:187], v[186:187], 0, v[180:181]
	global_load_dwordx4 v[168:171], v[186:187], off
	v_mul_lo_u32 v184, v184, s16
	v_add3_u32 v178, s23, v184, v180
	v_add_u32_e32 v182, 0x600, v78
	v_add_u32_e32 v183, 0x3000, v80
	v_ashrrev_i32_e32 v184, 4, v182
	v_add_u32_e32 v186, s15, v184
	v_ashrrev_i32_e32 v187, 31, v186
	v_lshlrev_b32_e32 v180, 1, v183
	v_lshlrev_b64 v[186:187], 8, v[186:187]
	v_and_b32_e32 v180, 0xf0, v180
	v_lshl_add_u64 v[186:187], s[98:99], 0, v[186:187]
	v_lshl_add_u64 v[186:187], v[186:187], 0, v[180:181]
	global_load_dwordx4 v[172:175], v[186:187], off
	v_mul_lo_u32 v184, v184, s16
	v_add3_u32 v179, s23, v184, v180
	s_lshl_b32 s0, s14, 7
	v_add_u32_e32 v126, s0, v82
	s_lshl_b32 s1, s13, 8
	v_ashrrev_i32_e32 v127, 31, v126
	v_or_b32_e32 v130, s1, v81
	v_readlane_b32 s52, v251, 9
	v_readlane_b32 s53, v251, 10
	v_readlane_b32 s60, v249, 21
	v_readlane_b32 s61, v249, 22
	v_readlane_b32 s62, v249, 23
	v_readlane_b32 s63, v249, 24
	v_lshlrev_b64 v[128:129], 13, v[126:127]
	v_lshlrev_b32_e32 v134, 2, v130
	v_lshlrev_b32_e32 v132, 1, v130
	v_mov_b32_e32 v133, 0
	v_lshl_add_u64 v[128:129], s[52:53], 0, v[128:129]
	s_mov_b64 s[0:1], 0x1000
	v_lshl_add_u64 v[128:129], v[128:129], 0, v[132:133]
	global_load_dwordx4 v[102:105], v134, s[60:61]
	v_lshl_add_u64 v[128:129], v[128:129], 0, s[0:1]
	global_load_dwordx4 v[106:109], v134, s[62:63]
	s_mov_b64 s[0:1], 0x20000
	global_load_dwordx4 v[110:113], v134, s[60:61] offset:16
	global_load_dwordx4 v[114:117], v134, s[62:63] offset:16
	global_load_dwordx4 v[118:121], v[128:129], off
	v_lshl_add_u64 v[128:129], v[128:129], 0, s[0:1]
	global_load_dwordx4 v[122:125], v[128:129], off
	v_lshl_add_u64 v[128:129], v[128:129], 0, s[0:1]
	global_load_dwordx4 v[200:203], v[128:129], off
	v_lshl_add_u64 v[128:129], v[128:129], 0, s[0:1]
	global_load_dwordx4 v[204:207], v[128:129], off
	v_lshl_add_u64 v[128:129], v[128:129], 0, s[0:1]
	global_load_dwordx4 v[208:211], v[128:129], off
	v_lshl_add_u64 v[128:129], v[128:129], 0, s[0:1]
	global_load_dwordx4 v[212:215], v[128:129], off
	v_lshl_add_u64 v[128:129], v[128:129], 0, s[0:1]
	global_load_dwordx4 v[216:219], v[128:129], off
	v_lshl_add_u64 v[128:129], v[128:129], 0, s[0:1]
	global_load_dwordx4 v[220:223], v[128:129], off
	s_barrier
	s_and_saveexec_b64 s[2:3], s[4:5]
	s_cbranch_execz .LBB0_146
	v_lshl_add_u32 v2, s14, 7, v78
	v_ashrrev_i32_e32 v3, 31, v2
	v_readlane_b32 s0, v251, 59
	v_lshlrev_b64 v[2:3], 6, v[2:3]
	v_readlane_b32 s1, v251, 60
	s_nop 1
	v_lshl_add_u64 v[14:15], s[0:1], 0, v[2:3]
	global_load_dwordx4 v[2:5], v[14:15], off
	global_load_dwordx4 v[6:9], v[14:15], off offset:16
	global_load_dwordx4 v[10:13], v[14:15], off offset:32
	s_nop 0
	global_load_dwordx4 v[14:17], v[14:15], off offset:48
	s_mov_b32 s0, 0x3a000000
	s_waitcnt vmcnt(0)
	v_add_f32_e32 v0, v2, v4
	s_waitcnt vmcnt(2)
	v_add_f32_e32 v2, v6, v8
	s_waitcnt vmcnt(1)
	v_add_f32_e32 v4, v10, v12
	s_waitcnt vmcnt(0)
	v_add_f32_e32 v6, v14, v16
	v_add_f32_e32 v0, v0, v2
	v_add_f32_e32 v2, v4, v6
	v_add_f32_e32 v3, v3, v5
	v_add_f32_e32 v5, v7, v9
	v_add_f32_e32 v7, v11, v13
	v_add_f32_e32 v8, v15, v17
	v_add_f32_e32 v0, v0, v2
	v_add_f32_e32 v3, v3, v5
	v_add_f32_e32 v4, v7, v8
	v_mul_f32_e32 v2, 0x3a000000, v0
	v_add_f32_e32 v3, v3, v4
	v_mul_f32_e32 v0, v2, v2
	v_fma_f32 v0, v3, s0, -v0
	v_max_f32_e32 v0, 0, v0
	v_add_f32_e32 v0, 0x3727c5ac, v0
	v_mul_f32_e32 v3, 0x4f800000, v0
	v_cmp_gt_f32_e32 vcc, s20, v0
	v_add_u32_e32 v4, 0, v80
	v_add_u32_e32 v4, 0x1a800, v4
	v_cndmask_b32_e32 v0, v0, v3, vcc
	v_sqrt_f32_e32 v3, v0
	s_nop 0
	v_add_u32_e32 v5, -1, v3
	v_add_u32_e32 v6, 1, v3
	v_fma_f32 v7, -v5, v3, v0
	v_fma_f32 v8, -v6, v3, v0
	v_cmp_ge_f32_e64 s[0:1], 0, v7
	s_nop 1
	v_cndmask_b32_e64 v3, v3, v5, s[0:1]
	v_cmp_lt_f32_e64 s[0:1], 0, v8
	s_nop 1
	v_cndmask_b32_e64 v3, v3, v6, s[0:1]
	v_mul_f32_e32 v5, 0x37800000, v3
	v_cndmask_b32_e32 v3, v3, v5, vcc
	v_cmp_class_f32_e32 vcc, v0, v156
	s_nop 1
	v_cndmask_b32_e32 v0, v3, v0, vcc
	v_div_scale_f32 v3, s[0:1], v0, v0, 1.0
	v_rcp_f32_e32 v5, v3
	v_div_scale_f32 v6, vcc, 1.0, v0, 1.0
	v_fma_f32 v7, -v3, v5, 1.0
	v_fmac_f32_e32 v5, v7, v5
	v_mul_f32_e32 v7, v6, v5
	v_fma_f32 v8, -v3, v7, v6
	v_fmac_f32_e32 v7, v8, v5
	v_fma_f32 v3, -v3, v7, v6
	v_div_fmas_f32 v3, v3, v5, v7
	v_div_fixup_f32 v3, v3, v0, 1.0
	ds_write_b64 v4, v[2:3]

.LBB0_148:
	s_waitcnt vmcnt(0)
	ds_write_b128 v176, v[160:163]
	ds_write_b128 v177, v[164:167]
	ds_write_b128 v178, v[168:171]
	ds_write_b128 v179, v[172:175]
.LBB0_149:
	s_or_b64 exec, exec, s[0:1]
	s_lshl_b32 s0, s14, 7
	v_add_u32_e32 v22, s0, v82
	s_lshl_b32 s1, s13, 8
	v_ashrrev_i32_e32 v23, 31, v22
	v_readlane_b32 s14, v251, 9
	v_or_b32_e32 v0, s1, v81
	v_lshlrev_b64 v[2:3], 13, v[22:23]
	v_readlane_b32 s15, v251, 10
	v_lshlrev_b32_e32 v10, 2, v0
	v_lshlrev_b32_e32 v0, 1, v0
	v_lshl_add_u64 v[2:3], s[14:15], 0, v[2:3]
	v_lshl_add_u64 v[18:19], v[2:3], 0, v[0:1]
	s_movk_i32 s16, 0x1000
	v_readlane_b32 s52, v249, 13
	v_add_co_u32_e32 v18, vcc, s16, v18
	v_readlane_b32 s60, v249, 21
	v_readlane_b32 s61, v249, 22
	v_readlane_b32 s62, v249, 23
	v_readlane_b32 s63, v249, 24
	v_addc_co_u32_e32 v19, vcc, 0, v19, vcc
	s_waitcnt lgkmcnt(0)
	s_barrier
	s_waitcnt vmcnt(0)
	v_mov_b64_e32 v[6:7], v[102:103]
	v_mov_b64_e32 v[8:9], v[104:105]
	v_mov_b64_e32 v[14:15], v[106:107]
	v_mov_b64_e32 v[16:17], v[108:109]
	v_mov_b64_e32 v[2:3], v[110:111]
	v_mov_b64_e32 v[4:5], v[112:113]
	v_mov_b64_e32 v[10:11], v[114:115]
	v_mov_b64_e32 v[12:13], v[116:117]
	s_add_i32 s2, 0, 0x1a800
	v_mov_b64_e32 v[30:31], v[118:119]
	v_mov_b64_e32 v[32:33], v[120:121]
	v_add_u32_e32 v19, s2, v83
	v_add_u32_e32 v18, 16, v22
	ds_read_b64 v[38:39], v19
	v_ashrrev_i32_e32 v19, 31, v18
	v_lshlrev_b64 v[18:19], 13, v[18:19]
	v_lshl_add_u64 v[18:19], s[14:15], 0, v[18:19]
	v_lshl_add_u64 v[18:19], v[18:19], 0, v[0:1]
	v_add_co_u32_e32 v18, vcc, s16, v18
	v_add_u32_e32 v20, 32, v22
	s_nop 0
	v_addc_co_u32_e32 v19, vcc, 0, v19, vcc
	v_mov_b64_e32 v[34:35], v[122:123]
	v_mov_b64_e32 v[36:37], v[124:125]
	v_add_u32_e32 v24, 48, v22
	v_ashrrev_i32_e32 v21, 31, v20
	v_ashrrev_i32_e32 v25, 31, v24
	v_add_u32_e32 v26, 64, v22
	v_add_u32_e32 v28, 0x50, v22
	v_lshlrev_b64 v[18:19], 13, v[20:21]
	v_lshlrev_b64 v[20:21], 13, v[24:25]
	v_ashrrev_i32_e32 v27, 31, v26
	v_ashrrev_i32_e32 v29, 31, v28
	v_lshl_add_u64 v[18:19], s[14:15], 0, v[18:19]
	v_lshl_add_u64 v[20:21], s[14:15], 0, v[20:21]
	v_lshlrev_b64 v[24:25], 13, v[26:27]
	v_lshlrev_b64 v[26:27], 13, v[28:29]
	v_lshl_add_u64 v[42:43], v[18:19], 0, v[0:1]
	v_lshl_add_u64 v[28:29], v[20:21], 0, v[0:1]
	v_lshl_add_u64 v[24:25], s[14:15], 0, v[24:25]
	v_lshl_add_u64 v[40:41], s[14:15], 0, v[26:27]
	v_lshl_add_u64 v[26:27], v[24:25], 0, v[0:1]
	v_lshl_add_u64 v[24:25], v[40:41], 0, v[0:1]
	s_mov_b32 s3, 0xffff0000
	v_readlane_b32 s53, v249, 14
	v_readlane_b32 s54, v249, 15
	v_readlane_b32 s55, v249, 16
	v_readlane_b32 s56, v249, 17
	v_readlane_b32 s57, v249, 18
	v_readlane_b32 s58, v249, 19
	v_readlane_b32 s59, v249, 20
	v_readlane_b32 s64, v249, 25
	v_readlane_b32 s65, v249, 26
	v_readlane_b32 s66, v249, 27
	v_readlane_b32 s67, v249, 28
	s_waitcnt vmcnt(0)
	v_mov_b32_e32 v18, v6
	v_mov_b32_e32 v19, v8
	s_waitcnt vmcnt(4)
	v_mov_b32_e32 v20, v14
	v_mov_b32_e32 v21, v16
	v_mov_b32_e32 v8, v7
	v_mov_b32_e32 v16, v15
	s_waitcnt vmcnt(3)
	v_mov_b32_e32 v6, v2
	v_mov_b32_e32 v7, v4
	s_waitcnt vmcnt(2)
	v_mov_b32_e32 v14, v10
	v_mov_b32_e32 v15, v12
	v_mov_b32_e32 v4, v3
	v_mov_b32_e32 v12, v11
	s_waitcnt vmcnt(1)
	v_lshlrev_b32_e32 v3, 16, v31
	v_lshlrev_b32_e32 v2, 16, v30
	v_and_b32_e32 v11, 0xffff0000, v31
	v_and_b32_e32 v10, 0xffff0000, v30
	v_lshlrev_b32_e32 v31, 16, v33
	v_lshlrev_b32_e32 v30, 16, v32
	v_and_b32_e32 v33, 0xffff0000, v33
	v_and_b32_e32 v32, 0xffff0000, v32
	s_waitcnt lgkmcnt(0)
	v_pk_add_f32 v[30:31], v[30:31], v[38:39] op_sel_hi:[1,0] neg_lo:[0,1] neg_hi:[0,1]
	v_pk_add_f32 v[2:3], v[2:3], v[38:39] op_sel_hi:[1,0] neg_lo:[0,1] neg_hi:[0,1]
	v_pk_add_f32 v[10:11], v[10:11], v[38:39] op_sel_hi:[1,0] neg_lo:[0,1] neg_hi:[0,1]
	v_pk_add_f32 v[32:33], v[32:33], v[38:39] op_sel_hi:[1,0] neg_lo:[0,1] neg_hi:[0,1]
	v_pk_mul_f32 v[30:31], v[30:31], v[38:39] op_sel:[0,1]
	v_pk_mul_f32 v[2:3], v[2:3], v[38:39] op_sel:[0,1]
	v_pk_mul_f32 v[10:11], v[10:11], v[38:39] op_sel:[0,1]
	v_pk_mul_f32 v[32:33], v[32:33], v[38:39] op_sel:[0,1]
	v_pk_fma_f32 v[38:39], v[6:7], v[30:31], v[14:15]
	v_add_co_u32_e32 v30, vcc, s16, v42
	v_pk_fma_f32 v[40:41], v[4:5], v[32:33], v[12:13]
	s_nop 0
	v_addc_co_u32_e32 v31, vcc, 0, v43, vcc
	v_mov_b64_e32 v[30:31], v[200:201]
	v_mov_b64_e32 v[32:33], v[202:203]
	v_pk_fma_f32 v[2:3], v[18:19], v[2:3], v[20:21]
	v_bfe_u32 v23, v41, 16, 1
	v_bfe_u32 v44, v40, 16, 1
	v_pk_fma_f32 v[10:11], v[8:9], v[10:11], v[16:17]
	v_add3_u32 v40, v40, v44, s87
	v_add3_u32 v23, v41, v23, s87
	v_bfe_u32 v41, v2, 16, 1
	v_bfe_u32 v42, v3, 16, 1
	v_bfe_u32 v43, v38, 16, 1
	v_bfe_u32 v44, v39, 16, 1
	v_bfe_u32 v45, v11, 16, 1
	v_bfe_u32 v46, v10, 16, 1
	v_add3_u32 v39, v39, v44, s87
	v_add3_u32 v38, v38, v43, s87
	v_add3_u32 v3, v3, v42, s87
	v_add3_u32 v2, v2, v41, s87
	v_add3_u32 v10, v10, v46, s87
	v_add3_u32 v11, v11, v45, s87
	v_lshrrev_b32_e32 v2, 16, v2
	v_lshrrev_b32_e32 v3, 16, v3
	v_lshrrev_b32_e32 v38, 16, v38
	v_lshrrev_b32_e32 v39, 16, v39
	v_and_or_b32 v41, v23, s3, v39
	v_and_or_b32 v40, v40, s3, v38
	v_and_or_b32 v39, v11, s3, v3
	v_and_or_b32 v38, v10, s3, v2
	ds_write_b128 v96, v[38:41]
	v_add_u32_e32 v2, s2, v84
	ds_read_b64 v[2:3], v2
	s_waitcnt vmcnt(1)
	v_lshlrev_b32_e32 v39, 16, v35
	v_lshlrev_b32_e32 v38, 16, v34
	v_and_b32_e32 v35, 0xffff0000, v35
	v_and_b32_e32 v34, 0xffff0000, v34
	s_waitcnt lgkmcnt(0)
	v_pk_add_f32 v[34:35], v[34:35], v[2:3] op_sel_hi:[1,0] neg_lo:[0,1] neg_hi:[0,1]
	v_add_co_u32_e32 v28, vcc, s16, v28
	v_pk_mul_f32 v[34:35], v[34:35], v[2:3] op_sel:[0,1]
	v_pk_add_f32 v[38:39], v[38:39], v[2:3] op_sel_hi:[1,0] neg_lo:[0,1] neg_hi:[0,1]
	v_pk_fma_f32 v[40:41], v[8:9], v[34:35], v[16:17]
	v_lshlrev_b32_e32 v35, 16, v37
	v_lshlrev_b32_e32 v34, 16, v36
	v_pk_add_f32 v[34:35], v[34:35], v[2:3] op_sel_hi:[1,0] neg_lo:[0,1] neg_hi:[0,1]
	v_addc_co_u32_e32 v29, vcc, 0, v29, vcc
	v_pk_mul_f32 v[34:35], v[34:35], v[2:3] op_sel:[0,1]
	v_pk_mul_f32 v[38:39], v[38:39], v[2:3] op_sel:[0,1]
	v_pk_fma_f32 v[42:43], v[6:7], v[34:35], v[14:15]
	v_and_b32_e32 v35, 0xffff0000, v37
	v_and_b32_e32 v34, 0xffff0000, v36
	v_pk_add_f32 v[34:35], v[34:35], v[2:3] op_sel_hi:[1,0] neg_lo:[0,1] neg_hi:[0,1]
	v_pk_fma_f32 v[38:39], v[18:19], v[38:39], v[20:21]
	v_pk_mul_f32 v[2:3], v[34:35], v[2:3] op_sel:[0,1]
	v_mov_b64_e32 v[34:35], v[204:205]
	v_mov_b64_e32 v[36:37], v[206:207]
	v_pk_fma_f32 v[2:3], v[4:5], v[2:3], v[12:13]
	v_bfe_u32 v45, v41, 16, 1
	v_bfe_u32 v23, v3, 16, 1
	v_bfe_u32 v44, v2, 16, 1
	v_bfe_u32 v46, v40, 16, 1
	v_add3_u32 v28, v40, v46, s87
	v_add3_u32 v29, v41, v45, s87
	v_add3_u32 v2, v2, v44, s87
	v_add3_u32 v3, v3, v23, s87
	v_bfe_u32 v23, v38, 16, 1
	v_bfe_u32 v40, v39, 16, 1
	v_bfe_u32 v41, v42, 16, 1
	v_bfe_u32 v44, v43, 16, 1
	v_add3_u32 v43, v43, v44, s87
	v_add3_u32 v41, v42, v41, s87
	v_add3_u32 v39, v39, v40, s87
	v_add3_u32 v23, v38, v23, s87
	v_lshrrev_b32_e32 v23, 16, v23
	v_lshrrev_b32_e32 v38, 16, v39
	v_lshrrev_b32_e32 v39, 16, v41
	v_lshrrev_b32_e32 v40, 16, v43
	v_and_or_b32 v41, v3, s3, v40
	v_and_or_b32 v40, v2, s3, v39
	v_and_or_b32 v39, v29, s3, v38
	v_and_or_b32 v38, v28, s3, v23
	ds_write_b128 v96, v[38:41] offset:9216
	v_add_u32_e32 v2, s2, v85
	ds_read_b64 v[2:3], v2
	s_waitcnt vmcnt(1)
	v_lshlrev_b32_e32 v29, 16, v31
	v_lshlrev_b32_e32 v28, 16, v30
	v_add_co_u32_e32 v26, vcc, s16, v26
	s_waitcnt lgkmcnt(0)
	v_pk_add_f32 v[28:29], v[28:29], v[2:3] op_sel_hi:[1,0] neg_lo:[0,1] neg_hi:[0,1]
	v_addc_co_u32_e32 v27, vcc, 0, v27, vcc
	v_pk_mul_f32 v[28:29], v[28:29], v[2:3] op_sel:[0,1]
	v_add_u32_e32 v10, 0x60, v22
	v_pk_fma_f32 v[38:39], v[18:19], v[28:29], v[20:21]
	v_and_b32_e32 v29, 0xffff0000, v31
	v_and_b32_e32 v28, 0xffff0000, v30
	v_pk_add_f32 v[28:29], v[28:29], v[2:3] op_sel_hi:[1,0] neg_lo:[0,1] neg_hi:[0,1]
	v_ashrrev_i32_e32 v11, 31, v10
	v_pk_mul_f32 v[28:29], v[28:29], v[2:3] op_sel:[0,1]
	v_lshlrev_b64 v[10:11], 13, v[10:11]
	v_pk_fma_f32 v[30:31], v[8:9], v[28:29], v[16:17]
	v_lshlrev_b32_e32 v29, 16, v33
	v_lshlrev_b32_e32 v28, 16, v32
	v_pk_add_f32 v[28:29], v[28:29], v[2:3] op_sel_hi:[1,0] neg_lo:[0,1] neg_hi:[0,1]
	v_bfe_u32 v42, v30, 16, 1
	v_pk_mul_f32 v[28:29], v[28:29], v[2:3] op_sel:[0,1]
	v_add3_u32 v30, v30, v42, s87
	v_pk_fma_f32 v[40:41], v[6:7], v[28:29], v[14:15]
	v_and_b32_e32 v29, 0xffff0000, v33
	v_and_b32_e32 v28, 0xffff0000, v32
	v_pk_add_f32 v[28:29], v[28:29], v[2:3] op_sel_hi:[1,0] neg_lo:[0,1] neg_hi:[0,1]
	v_bfe_u32 v33, v31, 16, 1
	v_pk_mul_f32 v[2:3], v[28:29], v[2:3] op_sel:[0,1]
	v_add3_u32 v31, v31, v33, s87
	v_pk_fma_f32 v[2:3], v[4:5], v[2:3], v[12:13]
	v_bfe_u32 v33, v40, 16, 1
	v_bfe_u32 v23, v3, 16, 1
	v_bfe_u32 v32, v2, 16, 1
	v_add3_u32 v2, v2, v32, s87
	v_add3_u32 v3, v3, v23, s87
	v_bfe_u32 v23, v38, 16, 1
	v_bfe_u32 v32, v39, 16, 1
	v_bfe_u32 v42, v41, 16, 1
	v_add3_u32 v41, v41, v42, s87
	v_add3_u32 v33, v40, v33, s87
	v_add3_u32 v32, v39, v32, s87
	v_add3_u32 v23, v38, v23, s87
	v_mov_b64_e32 v[26:27], v[208:209]
	v_mov_b64_e32 v[28:29], v[210:211]
	v_lshrrev_b32_e32 v23, 16, v23
	v_lshrrev_b32_e32 v38, 16, v32
	v_lshrrev_b32_e32 v32, 16, v33
	v_lshrrev_b32_e32 v33, 16, v41
	v_and_or_b32 v33, v3, s3, v33
	v_and_or_b32 v32, v2, s3, v32
	v_and_or_b32 v31, v31, s3, v38
	v_and_or_b32 v30, v30, s3, v23
	ds_write_b128 v96, v[30:33] offset:18432
	v_add_u32_e32 v2, s2, v86
	ds_read_b64 v[2:3], v2
	v_add_u32_e32 v38, 0x70, v22
	s_waitcnt vmcnt(1)
	v_lshlrev_b32_e32 v23, 16, v35
	v_lshlrev_b32_e32 v22, 16, v34
	v_lshl_add_u64 v[10:11], s[14:15], 0, v[10:11]
	s_waitcnt lgkmcnt(0)
	v_pk_add_f32 v[22:23], v[22:23], v[2:3] op_sel_hi:[1,0] neg_lo:[0,1] neg_hi:[0,1]
	v_lshl_add_u64 v[10:11], v[10:11], 0, v[0:1]
	v_pk_mul_f32 v[22:23], v[22:23], v[2:3] op_sel:[0,1]
	s_nop 0
	v_pk_fma_f32 v[30:31], v[18:19], v[22:23], v[20:21]
	v_and_b32_e32 v23, 0xffff0000, v35
	v_and_b32_e32 v22, 0xffff0000, v34
	v_pk_add_f32 v[22:23], v[22:23], v[2:3] op_sel_hi:[1,0] neg_lo:[0,1] neg_hi:[0,1]
	s_nop 0
	v_pk_mul_f32 v[22:23], v[22:23], v[2:3] op_sel:[0,1]
	s_nop 0
	v_pk_fma_f32 v[32:33], v[8:9], v[22:23], v[16:17]
	v_lshlrev_b32_e32 v23, 16, v37
	v_lshlrev_b32_e32 v22, 16, v36
	v_pk_add_f32 v[22:23], v[22:23], v[2:3] op_sel_hi:[1,0] neg_lo:[0,1] neg_hi:[0,1]
	v_bfe_u32 v39, v33, 16, 1
	v_pk_mul_f32 v[22:23], v[22:23], v[2:3] op_sel:[0,1]
	v_bfe_u32 v40, v32, 16, 1
	v_pk_fma_f32 v[34:35], v[6:7], v[22:23], v[14:15]
	v_and_b32_e32 v23, 0xffff0000, v37
	v_and_b32_e32 v22, 0xffff0000, v36
	v_pk_add_f32 v[22:23], v[22:23], v[2:3] op_sel_hi:[1,0] neg_lo:[0,1] neg_hi:[0,1]
	v_add3_u32 v40, v32, v40, s87
	v_pk_mul_f32 v[2:3], v[22:23], v[2:3] op_sel:[0,1]
	v_add_co_u32_e32 v22, vcc, s16, v24
	v_pk_fma_f32 v[2:3], v[4:5], v[2:3], v[12:13]
	s_nop 0
	v_addc_co_u32_e32 v23, vcc, 0, v25, vcc
	v_mov_b64_e32 v[22:23], v[212:213]
	v_mov_b64_e32 v[24:25], v[214:215]
	v_bfe_u32 v36, v3, 16, 1
	v_bfe_u32 v37, v2, 16, 1
	v_add3_u32 v39, v33, v39, s87
	v_add3_u32 v2, v2, v37, s87
	v_add3_u32 v3, v3, v36, s87
	v_bfe_u32 v32, v30, 16, 1
	v_bfe_u32 v33, v31, 16, 1
	v_bfe_u32 v36, v34, 16, 1
	v_bfe_u32 v37, v35, 16, 1
	v_add3_u32 v35, v35, v37, s87
	v_add3_u32 v34, v34, v36, s87
	v_add3_u32 v31, v31, v33, s87
	v_add3_u32 v30, v30, v32, s87
	v_lshrrev_b32_e32 v30, 16, v30
	v_lshrrev_b32_e32 v31, 16, v31
	v_lshrrev_b32_e32 v32, 16, v34
	v_lshrrev_b32_e32 v33, 16, v35
	v_and_or_b32 v33, v3, s3, v33
	v_and_or_b32 v32, v2, s3, v32
	v_and_or_b32 v31, v39, s3, v31
	v_and_or_b32 v30, v40, s3, v30
	ds_write_b128 v96, v[30:33] offset:27648
	v_add_u32_e32 v2, s2, v87
	ds_read_b64 v[2:3], v2
	v_ashrrev_i32_e32 v39, 31, v38
	v_add_co_u32_e32 v10, vcc, s16, v10
	v_lshlrev_b64 v[34:35], 13, v[38:39]
	s_nop 0
	v_addc_co_u32_e32 v11, vcc, 0, v11, vcc
	s_waitcnt vmcnt(1)
	v_lshlrev_b32_e32 v31, 16, v27
	v_lshlrev_b32_e32 v30, 16, v26
	v_and_b32_e32 v27, 0xffff0000, v27
	v_and_b32_e32 v26, 0xffff0000, v26
	s_waitcnt lgkmcnt(0)
	v_pk_add_f32 v[26:27], v[26:27], v[2:3] op_sel_hi:[1,0] neg_lo:[0,1] neg_hi:[0,1]
	v_pk_add_f32 v[30:31], v[30:31], v[2:3] op_sel_hi:[1,0] neg_lo:[0,1] neg_hi:[0,1]
	v_pk_mul_f32 v[26:27], v[26:27], v[2:3] op_sel:[0,1]
	v_pk_mul_f32 v[30:31], v[30:31], v[2:3] op_sel:[0,1]
	v_pk_fma_f32 v[32:33], v[8:9], v[26:27], v[16:17]
	v_lshlrev_b32_e32 v27, 16, v29
	v_lshlrev_b32_e32 v26, 16, v28
	v_pk_add_f32 v[26:27], v[26:27], v[2:3] op_sel_hi:[1,0] neg_lo:[0,1] neg_hi:[0,1]
	v_pk_fma_f32 v[30:31], v[18:19], v[30:31], v[20:21]
	v_pk_mul_f32 v[26:27], v[26:27], v[2:3] op_sel:[0,1]
	v_bfe_u32 v40, v33, 16, 1
	v_pk_fma_f32 v[36:37], v[6:7], v[26:27], v[14:15]
	v_and_b32_e32 v27, 0xffff0000, v29
	v_and_b32_e32 v26, 0xffff0000, v28
	v_pk_add_f32 v[26:27], v[26:27], v[2:3] op_sel_hi:[1,0] neg_lo:[0,1] neg_hi:[0,1]
	v_bfe_u32 v41, v32, 16, 1
	v_pk_mul_f32 v[2:3], v[26:27], v[2:3] op_sel:[0,1]
	v_mov_b64_e32 v[26:27], v[216:217]
	v_mov_b64_e32 v[28:29], v[218:219]
	v_pk_fma_f32 v[2:3], v[4:5], v[2:3], v[12:13]
	v_add3_u32 v10, v32, v41, s87
	v_bfe_u32 v38, v3, 16, 1
	v_bfe_u32 v39, v2, 16, 1
	v_add3_u32 v11, v33, v40, s87
	v_add3_u32 v2, v2, v39, s87
	v_add3_u32 v3, v3, v38, s87
	v_bfe_u32 v32, v30, 16, 1
	v_bfe_u32 v33, v31, 16, 1
	v_bfe_u32 v38, v36, 16, 1
	v_bfe_u32 v39, v37, 16, 1
	v_add3_u32 v37, v37, v39, s87
	v_add3_u32 v36, v36, v38, s87
	v_add3_u32 v31, v31, v33, s87
	v_add3_u32 v30, v30, v32, s87
	v_lshrrev_b32_e32 v30, 16, v30
	v_lshrrev_b32_e32 v31, 16, v31
	v_lshrrev_b32_e32 v32, 16, v36
	v_lshrrev_b32_e32 v33, 16, v37
	v_and_or_b32 v33, v3, s3, v33
	v_and_or_b32 v32, v2, s3, v32
	v_and_or_b32 v31, v11, s3, v31
	v_and_or_b32 v30, v10, s3, v30
	ds_write_b128 v96, v[30:33] offset:36864
	v_add_u32_e32 v2, s2, v88
	ds_read_b64 v[2:3], v2
	s_waitcnt vmcnt(1)
	v_lshlrev_b32_e32 v31, 16, v23
	v_lshlrev_b32_e32 v30, 16, v22
	v_and_b32_e32 v23, 0xffff0000, v23
	v_and_b32_e32 v22, 0xffff0000, v22
	s_waitcnt lgkmcnt(0)
	v_pk_add_f32 v[22:23], v[22:23], v[2:3] op_sel_hi:[1,0] neg_lo:[0,1] neg_hi:[0,1]
	v_lshl_add_u64 v[10:11], s[14:15], 0, v[34:35]
	v_pk_mul_f32 v[22:23], v[22:23], v[2:3] op_sel:[0,1]
	v_lshl_add_u64 v[10:11], v[10:11], 0, v[0:1]
	v_pk_fma_f32 v[32:33], v[8:9], v[22:23], v[16:17]
	v_lshlrev_b32_e32 v23, 16, v25
	v_lshlrev_b32_e32 v22, 16, v24
	v_pk_add_f32 v[22:23], v[22:23], v[2:3] op_sel_hi:[1,0] neg_lo:[0,1] neg_hi:[0,1]
	v_add_co_u32_e32 v10, vcc, s16, v10
	v_pk_mul_f32 v[22:23], v[22:23], v[2:3] op_sel:[0,1]
	v_pk_add_f32 v[30:31], v[30:31], v[2:3] op_sel_hi:[1,0] neg_lo:[0,1] neg_hi:[0,1]
	v_pk_fma_f32 v[34:35], v[6:7], v[22:23], v[14:15]
	v_and_b32_e32 v23, 0xffff0000, v25
	v_and_b32_e32 v22, 0xffff0000, v24
	v_pk_add_f32 v[22:23], v[22:23], v[2:3] op_sel_hi:[1,0] neg_lo:[0,1] neg_hi:[0,1]
	v_addc_co_u32_e32 v11, vcc, 0, v11, vcc
	v_pk_mul_f32 v[30:31], v[30:31], v[2:3] op_sel:[0,1]
	v_pk_mul_f32 v[2:3], v[22:23], v[2:3] op_sel:[0,1]
	v_mov_b64_e32 v[22:23], v[220:221]
	v_mov_b64_e32 v[24:25], v[222:223]
	v_pk_fma_f32 v[2:3], v[4:5], v[2:3], v[12:13]
	v_pk_fma_f32 v[30:31], v[18:19], v[30:31], v[20:21]
	v_bfe_u32 v0, v3, 16, 1
	v_bfe_u32 v10, v2, 16, 1
	v_bfe_u32 v11, v33, 16, 1
	v_bfe_u32 v36, v32, 16, 1
	v_add3_u32 v36, v32, v36, s87
	v_add3_u32 v11, v33, v11, s87
	v_add3_u32 v2, v2, v10, s87
	v_add3_u32 v0, v3, v0, s87
	v_bfe_u32 v3, v30, 16, 1
	v_bfe_u32 v10, v31, 16, 1
	v_bfe_u32 v32, v34, 16, 1
	v_bfe_u32 v33, v35, 16, 1
	v_add3_u32 v33, v35, v33, s87
	v_add3_u32 v32, v34, v32, s87
	v_add3_u32 v10, v31, v10, s87
	v_add3_u32 v3, v30, v3, s87
	v_lshrrev_b32_e32 v3, 16, v3
	v_lshrrev_b32_e32 v10, 16, v10
	v_lshrrev_b32_e32 v30, 16, v32
	v_lshrrev_b32_e32 v31, 16, v33
	v_and_or_b32 v33, v0, s3, v31
	v_and_or_b32 v32, v2, s3, v30
	v_and_or_b32 v31, v11, s3, v10
	v_and_or_b32 v30, v36, s3, v3
	ds_write_b128 v96, v[30:33] offset:46080
	v_add_u32_e32 v0, s2, v89
	ds_read_b64 v[2:3], v0
	s_waitcnt vmcnt(1)
	v_lshlrev_b32_e32 v11, 16, v27
	v_lshlrev_b32_e32 v10, 16, v26
	v_and_b32_e32 v27, 0xffff0000, v27
	v_and_b32_e32 v26, 0xffff0000, v26
	v_lshlrev_b32_e32 v31, 16, v29
	v_lshlrev_b32_e32 v30, 16, v28
	v_and_b32_e32 v29, 0xffff0000, v29
	v_and_b32_e32 v28, 0xffff0000, v28
	s_waitcnt lgkmcnt(0)
	v_pk_add_f32 v[10:11], v[10:11], v[2:3] op_sel_hi:[1,0] neg_lo:[0,1] neg_hi:[0,1]
	v_pk_add_f32 v[26:27], v[26:27], v[2:3] op_sel_hi:[1,0] neg_lo:[0,1] neg_hi:[0,1]
	v_pk_add_f32 v[30:31], v[30:31], v[2:3] op_sel_hi:[1,0] neg_lo:[0,1] neg_hi:[0,1]
	v_pk_add_f32 v[28:29], v[28:29], v[2:3] op_sel_hi:[1,0] neg_lo:[0,1] neg_hi:[0,1]
	v_pk_mul_f32 v[10:11], v[10:11], v[2:3] op_sel:[0,1]
	v_pk_mul_f32 v[26:27], v[26:27], v[2:3] op_sel:[0,1]
	v_pk_mul_f32 v[30:31], v[30:31], v[2:3] op_sel:[0,1]
	v_pk_mul_f32 v[2:3], v[28:29], v[2:3] op_sel:[0,1]
	v_pk_fma_f32 v[26:27], v[8:9], v[26:27], v[16:17]
	v_pk_fma_f32 v[2:3], v[4:5], v[2:3], v[12:13]
	v_pk_fma_f32 v[10:11], v[18:19], v[10:11], v[20:21]
	v_pk_fma_f32 v[30:31], v[6:7], v[30:31], v[14:15]
	v_bfe_u32 v0, v3, 16, 1
	v_bfe_u32 v28, v2, 16, 1
	v_bfe_u32 v29, v27, 16, 1
	v_bfe_u32 v32, v26, 16, 1
	v_add3_u32 v26, v26, v32, s87
	v_add3_u32 v27, v27, v29, s87
	v_add3_u32 v2, v2, v28, s87
	v_add3_u32 v0, v3, v0, s87
	v_bfe_u32 v3, v10, 16, 1
	v_bfe_u32 v28, v11, 16, 1
	v_bfe_u32 v29, v30, 16, 1
	v_bfe_u32 v32, v31, 16, 1
	v_add3_u32 v31, v31, v32, s87
	v_add3_u32 v29, v30, v29, s87
	v_add3_u32 v11, v11, v28, s87
	v_add3_u32 v3, v10, v3, s87
	v_lshrrev_b32_e32 v3, 16, v3
	v_lshrrev_b32_e32 v10, 16, v11
	v_lshrrev_b32_e32 v11, 16, v29
	v_lshrrev_b32_e32 v28, 16, v31
	v_and_or_b32 v29, v0, s3, v28
	v_and_or_b32 v28, v2, s3, v11
	v_and_or_b32 v27, v27, s3, v10
	v_and_or_b32 v26, v26, s3, v3
	ds_write_b128 v96, v[26:29] offset:55296
	v_add_u32_e32 v0, s2, v90
	ds_read_b64 v[2:3], v0
	s_movk_i32 s2, 0xff00
	s_waitcnt vmcnt(0)
	v_lshlrev_b32_e32 v11, 16, v23
	v_lshlrev_b32_e32 v10, 16, v22
	s_waitcnt lgkmcnt(0)
	v_pk_add_f32 v[10:11], v[10:11], v[2:3] op_sel_hi:[1,0] neg_lo:[0,1] neg_hi:[0,1]
	s_nop 0
	v_pk_mul_f32 v[10:11], v[10:11], v[2:3] op_sel:[0,1]
	s_nop 0
	v_pk_fma_f32 v[10:11], v[18:19], v[10:11], v[20:21]
	v_and_b32_e32 v19, 0xffff0000, v23
	v_and_b32_e32 v18, 0xffff0000, v22
	v_pk_add_f32 v[18:19], v[18:19], v[2:3] op_sel_hi:[1,0] neg_lo:[0,1] neg_hi:[0,1]
	s_nop 0
	v_pk_mul_f32 v[18:19], v[18:19], v[2:3] op_sel:[0,1]
	s_nop 0
	v_pk_fma_f32 v[8:9], v[8:9], v[18:19], v[16:17]
	v_lshlrev_b32_e32 v17, 16, v25
	v_lshlrev_b32_e32 v16, 16, v24
	v_pk_add_f32 v[16:17], v[16:17], v[2:3] op_sel_hi:[1,0] neg_lo:[0,1] neg_hi:[0,1]
	s_nop 0
	v_pk_mul_f32 v[16:17], v[16:17], v[2:3] op_sel:[0,1]
	s_nop 0
	v_pk_fma_f32 v[6:7], v[6:7], v[16:17], v[14:15]
	v_and_b32_e32 v15, 0xffff0000, v25
	v_and_b32_e32 v14, 0xffff0000, v24
	v_pk_add_f32 v[14:15], v[14:15], v[2:3] op_sel_hi:[1,0] neg_lo:[0,1] neg_hi:[0,1]
	s_nop 0
	v_pk_mul_f32 v[2:3], v[14:15], v[2:3] op_sel:[0,1]
	s_nop 0
	v_pk_fma_f32 v[2:3], v[4:5], v[2:3], v[12:13]
	v_bfe_u32 v5, v9, 16, 1
	v_bfe_u32 v0, v3, 16, 1
	v_bfe_u32 v4, v2, 16, 1
	v_bfe_u32 v12, v8, 16, 1
	v_add3_u32 v8, v8, v12, s87
	v_add3_u32 v9, v9, v5, s87
	v_add3_u32 v2, v2, v4, s87
	v_add3_u32 v0, v3, v0, s87
	v_bfe_u32 v3, v10, 16, 1
	v_bfe_u32 v4, v11, 16, 1
	v_bfe_u32 v5, v6, 16, 1
	v_bfe_u32 v12, v7, 16, 1
	v_add3_u32 v7, v7, v12, s87
	v_add3_u32 v5, v6, v5, s87
	v_add3_u32 v4, v11, v4, s87
	v_add3_u32 v3, v10, v3, s87
	v_lshrrev_b32_e32 v6, 16, v3
	v_lshrrev_b32_e32 v3, 16, v4
	v_lshrrev_b32_e32 v4, 16, v5
	v_lshrrev_b32_e32 v5, 16, v7
	v_and_or_b32 v5, v0, s3, v5
	v_and_or_b32 v4, v2, s3, v4
	v_and_or_b32 v3, v9, s3, v3
	v_and_or_b32 v2, v8, s3, v6
	ds_write_b128 v96, v[2:5] offset:64512
	v_mov_b32_e32 v2, 0
	v_mov_b32_e32 v0, v95
	v_mov_b32_e32 v3, v2
	v_mov_b32_e32 v4, v2
	v_mov_b32_e32 v5, v2
	v_mov_b32_e32 v6, v2
	v_mov_b32_e32 v7, v2
	v_mov_b32_e32 v8, v2
	v_mov_b32_e32 v9, v2
	v_mov_b32_e32 v10, v2
	v_mov_b32_e32 v11, v2
	v_mov_b32_e32 v12, v2
	v_mov_b32_e32 v13, v2
	v_mov_b32_e32 v14, v2
	v_mov_b32_e32 v15, v2
	v_mov_b32_e32 v16, v2
	v_mov_b32_e32 v17, v2
	v_mov_b32_e32 v18, v2
	v_mov_b32_e32 v19, v2
	v_mov_b32_e32 v20, v2
	v_mov_b32_e32 v21, v2
	v_mov_b32_e32 v22, v2
	v_mov_b32_e32 v23, v2
	v_mov_b32_e32 v24, v2
	v_mov_b32_e32 v25, v2
	v_mov_b32_e32 v26, v2
	v_mov_b32_e32 v27, v2
	v_mov_b32_e32 v28, v2
	v_mov_b32_e32 v29, v2
	v_mov_b32_e32 v30, v2
	v_mov_b32_e32 v31, v2
	v_mov_b32_e32 v32, v2
	v_mov_b32_e32 v33, v2
	v_mov_b32_e32 v34, v2
	v_mov_b32_e32 v35, v2
	v_mov_b32_e32 v36, v2
	v_mov_b32_e32 v37, v2
	v_mov_b32_e32 v38, v2
	v_mov_b32_e32 v39, v2
	v_mov_b32_e32 v40, v2
	v_mov_b32_e32 v41, v2
	v_mov_b32_e32 v42, v2
	v_mov_b32_e32 v43, v2
	v_mov_b32_e32 v44, v2
	v_mov_b32_e32 v45, v2
	v_mov_b32_e32 v46, v2
	v_mov_b32_e32 v47, v2
	v_mov_b32_e32 v48, v2
	v_mov_b32_e32 v49, v2
	v_mov_b32_e32 v50, v2
	v_mov_b32_e32 v51, v2
	v_mov_b32_e32 v52, v2
	v_mov_b32_e32 v53, v2
	v_mov_b32_e32 v54, v2
	v_mov_b32_e32 v55, v2
	v_mov_b32_e32 v56, v2
	v_mov_b32_e32 v57, v2
	v_mov_b32_e32 v58, v2
	v_mov_b32_e32 v59, v2
	v_mov_b32_e32 v60, v2
	v_mov_b32_e32 v61, v2
	v_mov_b32_e32 v62, v2
	v_mov_b32_e32 v63, v2
	v_mov_b32_e32 v64, v2
	v_mov_b32_e32 v65, v2
	s_lshl_b32 s80, s1, 1
	v_readlane_b32 s66, v249, 27
	v_readlane_b32 s67, v249, 28
	v_lshl_add_u64 v[196:197], v[66:67], 0, s[80:81]
	v_lshlrev_b32_e32 v198, 2, v79
	v_lshl_or_b32 v198, s13, 9, v198
	v_or_b32_e32 v200, s0, v79
	v_ashrrev_i32_e32 v201, 31, v200
	v_lshlrev_b64 v[200:201], 13, v[200:201]
	v_lshl_add_u64 v[200:201], v[196:197], 0, v[200:201]
	global_load_dwordx2 v[160:161], v[200:201], off
	global_load_dwordx2 v[162:163], v[200:201], off offset:16
	global_load_dwordx2 v[164:165], v[200:201], off offset:32
	global_load_dwordx2 v[166:167], v[200:201], off offset:48
	global_load_dword v192, v198, s[66:67]
	v_or_b32_e32 v200, s0, v91
	v_ashrrev_i32_e32 v201, 31, v200
	v_lshlrev_b64 v[200:201], 13, v[200:201]
	v_lshl_add_u64 v[200:201], v[196:197], 0, v[200:201]
	global_load_dwordx2 v[168:169], v[200:201], off
	global_load_dwordx2 v[170:171], v[200:201], off offset:16
	global_load_dwordx2 v[172:173], v[200:201], off offset:32
	global_load_dwordx2 v[174:175], v[200:201], off offset:48
	global_load_dword v193, v198, s[66:67] offset:128
	v_or_b32_e32 v200, s0, v92
	v_ashrrev_i32_e32 v201, 31, v200
	v_lshlrev_b64 v[200:201], 13, v[200:201]
	v_lshl_add_u64 v[200:201], v[196:197], 0, v[200:201]
	global_load_dwordx2 v[176:177], v[200:201], off
	global_load_dwordx2 v[178:179], v[200:201], off offset:16
	global_load_dwordx2 v[180:181], v[200:201], off offset:32
	global_load_dwordx2 v[182:183], v[200:201], off offset:48
	global_load_dword v194, v198, s[66:67] offset:256
	v_or_b32_e32 v200, s0, v93
	v_ashrrev_i32_e32 v201, 31, v200
	v_lshlrev_b64 v[200:201], 13, v[200:201]
	v_lshl_add_u64 v[200:201], v[196:197], 0, v[200:201]
	global_load_dwordx2 v[184:185], v[200:201], off
	global_load_dwordx2 v[186:187], v[200:201], off offset:16
	global_load_dwordx2 v[188:189], v[200:201], off offset:32
	global_load_dwordx2 v[190:191], v[200:201], off offset:48
	global_load_dword v195, v198, s[66:67] offset:384
	s_waitcnt lgkmcnt(0)
	s_barrier
